# speedup vs baseline: 1.0274x; 1.0016x over previous
.LBB0_27:
	s_mov_b32 s0, 0xfffa0000
	s_mov_b32 s1, -1
	v_lshl_add_u64 v[186:187], v[62:63], 0, s[0:1]
	global_load_dwordx4 v[120:123], v[186:187], off
	s_mov_b32 s0, 0xfffac000
	s_mov_b32 s1, -1
	v_lshl_add_u64 v[186:187], v[62:63], 0, s[0:1]
	global_load_dwordx4 v[124:127], v[186:187], off
	s_mov_b32 s0, 0xfffb8000
	s_mov_b32 s1, -1
	v_lshl_add_u64 v[186:187], v[62:63], 0, s[0:1]
	global_load_dwordx4 v[128:131], v[186:187], off
	s_mov_b32 s0, 0xfffc4000
	s_mov_b32 s1, -1
	v_lshl_add_u64 v[186:187], v[62:63], 0, s[0:1]
	global_load_dwordx4 v[132:135], v[186:187], off
	s_mov_b32 s0, 0xfffd0000
	s_mov_b32 s1, -1
	v_lshl_add_u64 v[186:187], v[62:63], 0, s[0:1]
	global_load_dwordx4 v[136:139], v[186:187], off
	s_mov_b32 s0, 0xfffdc000
	s_mov_b32 s1, -1
	v_lshl_add_u64 v[186:187], v[62:63], 0, s[0:1]
	global_load_dwordx4 v[140:143], v[186:187], off
	s_mov_b32 s0, 0xfffe8000
	s_mov_b32 s1, -1
	v_lshl_add_u64 v[186:187], v[62:63], 0, s[0:1]
	global_load_dwordx4 v[144:147], v[186:187], off
	s_mov_b32 s0, 0xffff4000
	s_mov_b32 s1, -1
	v_lshl_add_u64 v[186:187], v[62:63], 0, s[0:1]
	global_load_dwordx4 v[148:151], v[186:187], off
	s_mov_b32 s0, 0x0
	s_mov_b32 s1, 0
	v_lshl_add_u64 v[186:187], v[62:63], 0, s[0:1]
	global_load_dwordx4 v[152:155], v[186:187], off
	s_mov_b32 s0, 0xc000
	s_mov_b32 s1, 0
	v_lshl_add_u64 v[186:187], v[62:63], 0, s[0:1]
	global_load_dwordx4 v[156:159], v[186:187], off
	s_mov_b32 s0, 0x18000
	s_mov_b32 s1, 0
	v_lshl_add_u64 v[186:187], v[62:63], 0, s[0:1]
	global_load_dwordx4 v[160:163], v[186:187], off
	s_mov_b32 s0, 0x24000
	s_mov_b32 s1, 0
	v_lshl_add_u64 v[186:187], v[62:63], 0, s[0:1]
	global_load_dwordx4 v[164:167], v[186:187], off
	s_mov_b32 s0, 0x30000
	s_mov_b32 s1, 0
	v_lshl_add_u64 v[186:187], v[62:63], 0, s[0:1]
	global_load_dwordx4 v[168:171], v[186:187], off
	s_mov_b32 s0, 0x3c000
	s_mov_b32 s1, 0
	v_lshl_add_u64 v[186:187], v[62:63], 0, s[0:1]
	global_load_dwordx4 v[172:175], v[186:187], off
	s_mov_b32 s0, 0x48000
	s_mov_b32 s1, 0
	v_lshl_add_u64 v[186:187], v[62:63], 0, s[0:1]
	global_load_dwordx4 v[176:179], v[186:187], off
	s_mov_b32 s0, 0x54000
	s_mov_b32 s1, 0
	v_lshl_add_u64 v[186:187], v[62:63], 0, s[0:1]
	global_load_dwordx4 v[188:191], v[186:187], off
	s_mov_b32 s0, 0xfffa0000
	v_add_u32_e32 v82, s2, v79
	s_nop 0
	ds_read_b128 v[50:53], v82
	ds_read_b128 v[46:49], v82 offset:16
	ds_read_b128 v[42:45], v82 offset:32
	ds_read_b128 v[2:5], v82 offset:48
	s_mov_b32 s0, 0xfffac000
	s_add_i32 s2, s2, 64
	s_cmpk_lg_i32 s2, 0x200
	s_waitcnt vmcnt(15) lgkmcnt(3)
	v_pk_fma_f32 v[54:55], v[122:123], v[50:51], v[40:41] op_sel_hi:[1,0,1]
	v_pk_fma_f32 v[68:69], v[120:121], v[50:51], v[38:39] op_sel_hi:[1,0,1]
	ds_read_b128 v[38:41], v82 offset:8192
	s_waitcnt lgkmcnt(0)
	v_pk_fma_f32 v[70:71], v[122:123], v[38:39], v[36:37] op_sel_hi:[1,0,1]
	v_pk_fma_f32 v[84:85], v[120:121], v[38:39], v[34:35] op_sel_hi:[1,0,1]
	ds_read_b128 v[34:37], v82 offset:16384
	s_waitcnt lgkmcnt(0)
	v_pk_fma_f32 v[86:87], v[122:123], v[34:35], v[32:33] op_sel_hi:[1,0,1]
	v_pk_fma_f32 v[88:89], v[120:121], v[34:35], v[30:31] op_sel_hi:[1,0,1]
	ds_read_b128 v[30:33], v82 offset:24576
	s_waitcnt lgkmcnt(0)
	v_pk_fma_f32 v[90:91], v[122:123], v[30:31], v[28:29] op_sel_hi:[1,0,1]
	v_pk_fma_f32 v[92:93], v[120:121], v[30:31], v[26:27] op_sel_hi:[1,0,1]
	ds_read_b128 v[26:29], v82 offset:32768
	s_waitcnt lgkmcnt(0)
	v_pk_fma_f32 v[94:95], v[122:123], v[26:27], v[24:25] op_sel_hi:[1,0,1]
	v_pk_fma_f32 v[96:97], v[120:121], v[26:27], v[22:23] op_sel_hi:[1,0,1]
	ds_read_b128 v[22:25], v82 offset:40960
	s_waitcnt lgkmcnt(0)
	v_pk_fma_f32 v[98:99], v[122:123], v[22:23], v[20:21] op_sel_hi:[1,0,1]
	v_pk_fma_f32 v[100:101], v[120:121], v[22:23], v[18:19] op_sel_hi:[1,0,1]
	ds_read_b128 v[18:21], v82 offset:49152
	s_waitcnt lgkmcnt(0)
	v_pk_fma_f32 v[102:103], v[122:123], v[18:19], v[16:17] op_sel_hi:[1,0,1]
	v_pk_fma_f32 v[104:105], v[120:121], v[18:19], v[14:15] op_sel_hi:[1,0,1]
	ds_read_b128 v[14:17], v82 offset:57344
	s_waitcnt lgkmcnt(0)
	v_pk_fma_f32 v[108:109], v[120:121], v[14:15], v[10:11] op_sel_hi:[1,0,1]
	v_add_u32_e32 v10, 0x10000, v82
	v_pk_fma_f32 v[106:107], v[122:123], v[14:15], v[12:13] op_sel_hi:[1,0,1]
	ds_read_b128 v[10:13], v10
	s_waitcnt lgkmcnt(0)
	v_pk_fma_f32 v[64:65], v[120:121], v[10:11], v[6:7] op_sel_hi:[1,0,1]
	v_pk_fma_f32 v[66:67], v[122:123], v[10:11], v[8:9] op_sel_hi:[1,0,1]
	s_nop 0
	s_mov_b32 s0, 0xfffb8000
	s_waitcnt vmcnt(14)
	v_pk_fma_f32 v[54:55], v[126:127], v[50:51], v[54:55] op_sel:[0,1,0]
	v_pk_fma_f32 v[50:51], v[124:125], v[50:51], v[68:69] op_sel:[0,1,0]
	v_pk_fma_f32 v[68:69], v[126:127], v[38:39], v[70:71] op_sel:[0,1,0]
	v_pk_fma_f32 v[38:39], v[124:125], v[38:39], v[84:85] op_sel:[0,1,0]
	v_pk_fma_f32 v[70:71], v[126:127], v[34:35], v[86:87] op_sel:[0,1,0]
	v_pk_fma_f32 v[34:35], v[124:125], v[34:35], v[88:89] op_sel:[0,1,0]
	v_pk_fma_f32 v[84:85], v[126:127], v[30:31], v[90:91] op_sel:[0,1,0]
	v_pk_fma_f32 v[30:31], v[124:125], v[30:31], v[92:93] op_sel:[0,1,0]
	v_pk_fma_f32 v[86:87], v[126:127], v[26:27], v[94:95] op_sel:[0,1,0]
	v_pk_fma_f32 v[26:27], v[124:125], v[26:27], v[96:97] op_sel:[0,1,0]
	v_pk_fma_f32 v[88:89], v[126:127], v[22:23], v[98:99] op_sel:[0,1,0]
	v_pk_fma_f32 v[22:23], v[124:125], v[22:23], v[100:101] op_sel:[0,1,0]
	v_pk_fma_f32 v[90:91], v[126:127], v[18:19], v[102:103] op_sel:[0,1,0]
	v_pk_fma_f32 v[18:19], v[124:125], v[18:19], v[104:105] op_sel:[0,1,0]
	v_pk_fma_f32 v[92:93], v[126:127], v[14:15], v[106:107] op_sel:[0,1,0]
	v_pk_fma_f32 v[14:15], v[124:125], v[14:15], v[108:109] op_sel:[0,1,0]
	v_pk_fma_f32 v[66:67], v[126:127], v[10:11], v[66:67] op_sel:[0,1,0]
	v_pk_fma_f32 v[10:11], v[124:125], v[10:11], v[64:65] op_sel:[0,1,0]
	s_nop 1
	s_mov_b32 s0, 0xfffc4000
	s_waitcnt vmcnt(13)
	v_pk_fma_f32 v[50:51], v[128:129], v[52:53], v[50:51] op_sel_hi:[1,0,1]
	v_pk_fma_f32 v[38:39], v[128:129], v[40:41], v[38:39] op_sel_hi:[1,0,1]
	v_pk_fma_f32 v[34:35], v[128:129], v[36:37], v[34:35] op_sel_hi:[1,0,1]
	v_pk_fma_f32 v[30:31], v[128:129], v[32:33], v[30:31] op_sel_hi:[1,0,1]
	v_pk_fma_f32 v[26:27], v[128:129], v[28:29], v[26:27] op_sel_hi:[1,0,1]
	v_pk_fma_f32 v[22:23], v[128:129], v[24:25], v[22:23] op_sel_hi:[1,0,1]
	v_pk_fma_f32 v[18:19], v[128:129], v[20:21], v[18:19] op_sel_hi:[1,0,1]
	v_pk_fma_f32 v[14:15], v[128:129], v[16:17], v[14:15] op_sel_hi:[1,0,1]
	v_pk_fma_f32 v[10:11], v[128:129], v[12:13], v[10:11] op_sel_hi:[1,0,1]
	v_pk_fma_f32 v[54:55], v[130:131], v[52:53], v[54:55] op_sel_hi:[1,0,1]
	s_nop 0
	v_pk_fma_f32 v[64:65], v[130:131], v[40:41], v[68:69] op_sel_hi:[1,0,1]
	v_pk_fma_f32 v[68:69], v[130:131], v[36:37], v[70:71] op_sel_hi:[1,0,1]
	v_pk_fma_f32 v[70:71], v[130:131], v[32:33], v[84:85] op_sel_hi:[1,0,1]
	v_pk_fma_f32 v[84:85], v[130:131], v[28:29], v[86:87] op_sel_hi:[1,0,1]
	v_pk_fma_f32 v[86:87], v[130:131], v[24:25], v[88:89] op_sel_hi:[1,0,1]
	v_pk_fma_f32 v[88:89], v[130:131], v[20:21], v[90:91] op_sel_hi:[1,0,1]
	v_pk_fma_f32 v[90:91], v[130:131], v[16:17], v[92:93] op_sel_hi:[1,0,1]
	v_pk_fma_f32 v[66:67], v[130:131], v[12:13], v[66:67] op_sel_hi:[1,0,1]
	v_mov_b32_e32 v12, v53
	s_mov_b32 s0, 0xfffd0000
	s_waitcnt vmcnt(12)
	v_pk_fma_f32 v[52:53], v[134:135], v[12:13], v[54:55] op_sel_hi:[1,0,1]
	v_pk_fma_f32 v[50:51], v[132:133], v[12:13], v[50:51] op_sel_hi:[1,0,1]
	v_mov_b32_e32 v12, v41
	v_pk_fma_f32 v[54:55], v[134:135], v[12:13], v[64:65] op_sel_hi:[1,0,1]
	v_pk_fma_f32 v[64:65], v[132:133], v[12:13], v[38:39] op_sel_hi:[1,0,1]
	v_mov_b32_e32 v12, v37
	v_pk_fma_f32 v[36:37], v[134:135], v[12:13], v[68:69] op_sel_hi:[1,0,1]
	v_pk_fma_f32 v[34:35], v[132:133], v[12:13], v[34:35] op_sel_hi:[1,0,1]
	v_mov_b32_e32 v12, v33
	v_pk_fma_f32 v[32:33], v[134:135], v[12:13], v[70:71] op_sel_hi:[1,0,1]
	v_pk_fma_f32 v[30:31], v[132:133], v[12:13], v[30:31] op_sel_hi:[1,0,1]
	v_mov_b32_e32 v12, v29
	v_pk_fma_f32 v[28:29], v[134:135], v[12:13], v[84:85] op_sel_hi:[1,0,1]
	v_pk_fma_f32 v[26:27], v[132:133], v[12:13], v[26:27] op_sel_hi:[1,0,1]
	v_mov_b32_e32 v12, v25
	v_pk_fma_f32 v[68:69], v[134:135], v[12:13], v[86:87] op_sel_hi:[1,0,1]
	v_pk_fma_f32 v[70:71], v[132:133], v[12:13], v[22:23] op_sel_hi:[1,0,1]
	v_mov_b32_e32 v12, v21
	v_pk_fma_f32 v[84:85], v[134:135], v[12:13], v[88:89] op_sel_hi:[1,0,1]
	v_pk_fma_f32 v[86:87], v[132:133], v[12:13], v[18:19] op_sel_hi:[1,0,1]
	v_mov_b32_e32 v12, v17
	v_pk_fma_f32 v[88:89], v[134:135], v[12:13], v[90:91] op_sel_hi:[1,0,1]
	v_pk_fma_f32 v[90:91], v[132:133], v[12:13], v[14:15] op_sel_hi:[1,0,1]
	v_mov_b32_e32 v12, v13
	v_pk_fma_f32 v[92:93], v[132:133], v[12:13], v[10:11] op_sel_hi:[1,0,1]
	v_pk_fma_f32 v[66:67], v[134:135], v[12:13], v[66:67] op_sel_hi:[1,0,1]
	s_nop 0
	ds_read_b128 v[10:13], v82 offset:16400
	ds_read_b128 v[14:17], v82 offset:24592
	ds_read_b128 v[18:21], v82 offset:32784
	ds_read_b128 v[6:9], v82 offset:8208
	ds_read_b128 v[22:25], v82 offset:40976
	s_mov_b32 s0, 0xfffdc000
	s_waitcnt vmcnt(11) lgkmcnt(4)
	v_pk_fma_f32 v[96:97], v[136:137], v[10:11], v[34:35] op_sel_hi:[1,0,1]
	v_add_u32_e32 v34, 0x10010, v82
	v_pk_fma_f32 v[94:95], v[138:139], v[10:11], v[36:37] op_sel_hi:[1,0,1]
	s_waitcnt lgkmcnt(3)
	v_pk_fma_f32 v[98:99], v[138:139], v[14:15], v[32:33] op_sel_hi:[1,0,1]
	v_pk_fma_f32 v[100:101], v[136:137], v[14:15], v[30:31] op_sel_hi:[1,0,1]
	ds_read_b128 v[30:33], v82 offset:57360
	ds_read_b128 v[34:37], v34
	s_waitcnt lgkmcnt(4)
	v_pk_fma_f32 v[102:103], v[138:139], v[18:19], v[28:29] op_sel_hi:[1,0,1]
	v_pk_fma_f32 v[104:105], v[136:137], v[18:19], v[26:27] op_sel_hi:[1,0,1]
	ds_read_b128 v[26:29], v82 offset:49168
	v_pk_fma_f32 v[50:51], v[136:137], v[46:47], v[50:51] op_sel_hi:[1,0,1]
	s_waitcnt lgkmcnt(4)
	v_pk_fma_f32 v[64:65], v[136:137], v[6:7], v[64:65] op_sel_hi:[1,0,1]
	s_waitcnt lgkmcnt(3)
	v_pk_fma_f32 v[70:71], v[136:137], v[22:23], v[70:71] op_sel_hi:[1,0,1]
	s_waitcnt lgkmcnt(2)
	v_pk_fma_f32 v[90:91], v[136:137], v[30:31], v[90:91] op_sel_hi:[1,0,1]
	s_waitcnt lgkmcnt(0)
	v_pk_fma_f32 v[108:109], v[136:137], v[26:27], v[86:87] op_sel_hi:[1,0,1]
	v_pk_fma_f32 v[92:93], v[136:137], v[34:35], v[92:93] op_sel_hi:[1,0,1]
	v_pk_fma_f32 v[106:107], v[138:139], v[26:27], v[84:85] op_sel_hi:[1,0,1]
	s_nop 0
	v_pk_fma_f32 v[52:53], v[138:139], v[46:47], v[52:53] op_sel_hi:[1,0,1]
	v_pk_fma_f32 v[54:55], v[138:139], v[6:7], v[54:55] op_sel_hi:[1,0,1]
	v_pk_fma_f32 v[68:69], v[138:139], v[22:23], v[68:69] op_sel_hi:[1,0,1]
	v_pk_fma_f32 v[88:89], v[138:139], v[30:31], v[88:89] op_sel_hi:[1,0,1]
	v_pk_fma_f32 v[110:111], v[138:139], v[34:35], v[66:67] op_sel_hi:[1,0,1]
	s_mov_b32 s0, 0xfffe8000
	s_waitcnt vmcnt(10)
	v_pk_fma_f32 v[38:39], v[142:143], v[46:47], v[52:53] op_sel:[0,1,0]
	v_pk_fma_f32 v[40:41], v[140:141], v[46:47], v[50:51] op_sel:[0,1,0]
	v_pk_fma_f32 v[46:47], v[142:143], v[6:7], v[54:55] op_sel:[0,1,0]
	v_pk_fma_f32 v[6:7], v[140:141], v[6:7], v[64:65] op_sel:[0,1,0]
	v_pk_fma_f32 v[50:51], v[142:143], v[10:11], v[94:95] op_sel:[0,1,0]
	v_pk_fma_f32 v[10:11], v[140:141], v[10:11], v[96:97] op_sel:[0,1,0]
	v_pk_fma_f32 v[52:53], v[142:143], v[14:15], v[98:99] op_sel:[0,1,0]
	v_pk_fma_f32 v[14:15], v[140:141], v[14:15], v[100:101] op_sel:[0,1,0]
	v_pk_fma_f32 v[54:55], v[142:143], v[18:19], v[102:103] op_sel:[0,1,0]
	v_pk_fma_f32 v[18:19], v[140:141], v[18:19], v[104:105] op_sel:[0,1,0]
	v_pk_fma_f32 v[64:65], v[142:143], v[22:23], v[68:69] op_sel:[0,1,0]
	v_pk_fma_f32 v[22:23], v[140:141], v[22:23], v[70:71] op_sel:[0,1,0]
	v_pk_fma_f32 v[66:67], v[142:143], v[26:27], v[106:107] op_sel:[0,1,0]
	v_pk_fma_f32 v[26:27], v[140:141], v[26:27], v[108:109] op_sel:[0,1,0]
	v_pk_fma_f32 v[68:69], v[142:143], v[30:31], v[88:89] op_sel:[0,1,0]
	v_pk_fma_f32 v[30:31], v[140:141], v[30:31], v[90:91] op_sel:[0,1,0]
	v_pk_fma_f32 v[70:71], v[142:143], v[34:35], v[110:111] op_sel:[0,1,0]
	v_pk_fma_f32 v[34:35], v[140:141], v[34:35], v[92:93] op_sel:[0,1,0]
	s_nop 1
	s_mov_b32 s0, 0xffff4000
	s_waitcnt vmcnt(9)
	v_pk_fma_f32 v[88:89], v[146:147], v[48:49], v[38:39] op_sel_hi:[1,0,1]
	v_pk_fma_f32 v[90:91], v[144:145], v[48:49], v[40:41] op_sel_hi:[1,0,1]
	s_nop 0
	v_pk_fma_f32 v[46:47], v[146:147], v[8:9], v[46:47] op_sel_hi:[1,0,1]
	v_pk_fma_f32 v[6:7], v[144:145], v[8:9], v[6:7] op_sel_hi:[1,0,1]
	v_mov_b32_e32 v8, v49
	v_pk_fma_f32 v[10:11], v[144:145], v[12:13], v[10:11] op_sel_hi:[1,0,1]
	v_pk_fma_f32 v[14:15], v[144:145], v[16:17], v[14:15] op_sel_hi:[1,0,1]
	v_pk_fma_f32 v[18:19], v[144:145], v[20:21], v[18:19] op_sel_hi:[1,0,1]
	v_pk_fma_f32 v[22:23], v[144:145], v[24:25], v[22:23] op_sel_hi:[1,0,1]
	v_pk_fma_f32 v[26:27], v[144:145], v[28:29], v[26:27] op_sel_hi:[1,0,1]
	v_pk_fma_f32 v[30:31], v[144:145], v[32:33], v[30:31] op_sel_hi:[1,0,1]
	v_pk_fma_f32 v[34:35], v[144:145], v[36:37], v[34:35] op_sel_hi:[1,0,1]
	v_pk_fma_f32 v[50:51], v[146:147], v[12:13], v[50:51] op_sel_hi:[1,0,1]
	v_pk_fma_f32 v[52:53], v[146:147], v[16:17], v[52:53] op_sel_hi:[1,0,1]
	v_pk_fma_f32 v[54:55], v[146:147], v[20:21], v[54:55] op_sel_hi:[1,0,1]
	v_pk_fma_f32 v[64:65], v[146:147], v[24:25], v[64:65] op_sel_hi:[1,0,1]
	v_pk_fma_f32 v[66:67], v[146:147], v[28:29], v[66:67] op_sel_hi:[1,0,1]
	v_pk_fma_f32 v[68:69], v[146:147], v[32:33], v[68:69] op_sel_hi:[1,0,1]
	v_pk_fma_f32 v[70:71], v[146:147], v[36:37], v[70:71] op_sel_hi:[1,0,1]
	s_waitcnt vmcnt(8)
	v_pk_fma_f32 v[48:49], v[150:151], v[8:9], v[88:89] op_sel_hi:[1,0,1]
	v_pk_fma_f32 v[84:85], v[148:149], v[8:9], v[90:91] op_sel_hi:[1,0,1]
	v_mov_b32_e32 v8, v9
	v_pk_fma_f32 v[86:87], v[148:149], v[8:9], v[6:7] op_sel_hi:[1,0,1]
	v_mov_b32_e32 v6, v13
	v_pk_fma_f32 v[50:51], v[150:151], v[6:7], v[50:51] op_sel_hi:[1,0,1]
	v_pk_fma_f32 v[88:89], v[148:149], v[6:7], v[10:11] op_sel_hi:[1,0,1]
	v_mov_b32_e32 v6, v17
	v_pk_fma_f32 v[52:53], v[150:151], v[6:7], v[52:53] op_sel_hi:[1,0,1]
	v_pk_fma_f32 v[90:91], v[148:149], v[6:7], v[14:15] op_sel_hi:[1,0,1]
	v_mov_b32_e32 v6, v21
	v_pk_fma_f32 v[54:55], v[150:151], v[6:7], v[54:55] op_sel_hi:[1,0,1]
	v_pk_fma_f32 v[92:93], v[148:149], v[6:7], v[18:19] op_sel_hi:[1,0,1]
	v_mov_b32_e32 v6, v25
	v_pk_fma_f32 v[64:65], v[150:151], v[6:7], v[64:65] op_sel_hi:[1,0,1]
	v_pk_fma_f32 v[94:95], v[148:149], v[6:7], v[22:23] op_sel_hi:[1,0,1]
	v_mov_b32_e32 v6, v29
	v_pk_fma_f32 v[66:67], v[150:151], v[6:7], v[66:67] op_sel_hi:[1,0,1]
	v_pk_fma_f32 v[96:97], v[148:149], v[6:7], v[26:27] op_sel_hi:[1,0,1]
	v_mov_b32_e32 v6, v33
	v_pk_fma_f32 v[68:69], v[150:151], v[6:7], v[68:69] op_sel_hi:[1,0,1]
	v_pk_fma_f32 v[98:99], v[148:149], v[6:7], v[30:31] op_sel_hi:[1,0,1]
	v_mov_b32_e32 v6, v37
	v_pk_fma_f32 v[46:47], v[150:151], v[8:9], v[46:47] op_sel_hi:[1,0,1]
	v_pk_fma_f32 v[70:71], v[150:151], v[6:7], v[70:71] op_sel_hi:[1,0,1]
	v_pk_fma_f32 v[100:101], v[148:149], v[6:7], v[34:35] op_sel_hi:[1,0,1]
	v_add_u32_e32 v34, 0x10020, v82
	ds_read_b128 v[6:9], v82 offset:8224
	ds_read_b128 v[30:33], v82 offset:57376
	ds_read_b128 v[10:13], v82 offset:16416
	ds_read_b128 v[14:17], v82 offset:24608
	ds_read_b128 v[18:21], v82 offset:32800
	ds_read_b128 v[34:37], v34
	ds_read_b128 v[22:25], v82 offset:40992
	ds_read_b128 v[26:29], v82 offset:49184
	s_waitcnt vmcnt(7)
	v_pk_fma_f32 v[84:85], v[152:153], v[42:43], v[84:85] op_sel_hi:[1,0,1]
	s_waitcnt lgkmcnt(7)
	v_pk_fma_f32 v[86:87], v[152:153], v[6:7], v[86:87] op_sel_hi:[1,0,1]
	s_waitcnt lgkmcnt(5)
	v_pk_fma_f32 v[88:89], v[152:153], v[10:11], v[88:89] op_sel_hi:[1,0,1]
	s_waitcnt lgkmcnt(4)
	v_pk_fma_f32 v[90:91], v[152:153], v[14:15], v[90:91] op_sel_hi:[1,0,1]
	s_waitcnt lgkmcnt(3)
	v_pk_fma_f32 v[92:93], v[152:153], v[18:19], v[92:93] op_sel_hi:[1,0,1]
	s_waitcnt lgkmcnt(1)
	v_pk_fma_f32 v[94:95], v[152:153], v[22:23], v[94:95] op_sel_hi:[1,0,1]
	s_waitcnt lgkmcnt(0)
	v_pk_fma_f32 v[96:97], v[152:153], v[26:27], v[96:97] op_sel_hi:[1,0,1]
	v_pk_fma_f32 v[98:99], v[152:153], v[30:31], v[98:99] op_sel_hi:[1,0,1]
	v_pk_fma_f32 v[100:101], v[152:153], v[34:35], v[100:101] op_sel_hi:[1,0,1]
	v_pk_fma_f32 v[48:49], v[154:155], v[42:43], v[48:49] op_sel_hi:[1,0,1]
	s_nop 0
	v_pk_fma_f32 v[46:47], v[154:155], v[6:7], v[46:47] op_sel_hi:[1,0,1]
	v_pk_fma_f32 v[50:51], v[154:155], v[10:11], v[50:51] op_sel_hi:[1,0,1]
	v_pk_fma_f32 v[52:53], v[154:155], v[14:15], v[52:53] op_sel_hi:[1,0,1]
	v_pk_fma_f32 v[54:55], v[154:155], v[18:19], v[54:55] op_sel_hi:[1,0,1]
	v_pk_fma_f32 v[64:65], v[154:155], v[22:23], v[64:65] op_sel_hi:[1,0,1]
	v_pk_fma_f32 v[66:67], v[154:155], v[26:27], v[66:67] op_sel_hi:[1,0,1]
	v_pk_fma_f32 v[68:69], v[154:155], v[30:31], v[68:69] op_sel_hi:[1,0,1]
	v_pk_fma_f32 v[70:71], v[154:155], v[34:35], v[70:71] op_sel_hi:[1,0,1]
	s_waitcnt vmcnt(6)
	v_pk_fma_f32 v[48:49], v[158:159], v[42:43], v[48:49] op_sel:[0,1,0]
	v_pk_fma_f32 v[42:43], v[156:157], v[42:43], v[84:85] op_sel:[0,1,0]
	v_pk_fma_f32 v[46:47], v[158:159], v[6:7], v[46:47] op_sel:[0,1,0]
	v_pk_fma_f32 v[6:7], v[156:157], v[6:7], v[86:87] op_sel:[0,1,0]
	v_pk_fma_f32 v[50:51], v[158:159], v[10:11], v[50:51] op_sel:[0,1,0]
	v_pk_fma_f32 v[10:11], v[156:157], v[10:11], v[88:89] op_sel:[0,1,0]
	v_pk_fma_f32 v[52:53], v[158:159], v[14:15], v[52:53] op_sel:[0,1,0]
	v_pk_fma_f32 v[14:15], v[156:157], v[14:15], v[90:91] op_sel:[0,1,0]
	v_pk_fma_f32 v[54:55], v[158:159], v[18:19], v[54:55] op_sel:[0,1,0]
	v_pk_fma_f32 v[18:19], v[156:157], v[18:19], v[92:93] op_sel:[0,1,0]
	v_pk_fma_f32 v[64:65], v[158:159], v[22:23], v[64:65] op_sel:[0,1,0]
	v_pk_fma_f32 v[22:23], v[156:157], v[22:23], v[94:95] op_sel:[0,1,0]
	v_pk_fma_f32 v[66:67], v[158:159], v[26:27], v[66:67] op_sel:[0,1,0]
	v_pk_fma_f32 v[26:27], v[156:157], v[26:27], v[96:97] op_sel:[0,1,0]
	v_pk_fma_f32 v[68:69], v[158:159], v[30:31], v[68:69] op_sel:[0,1,0]
	v_pk_fma_f32 v[30:31], v[156:157], v[30:31], v[98:99] op_sel:[0,1,0]
	v_pk_fma_f32 v[70:71], v[158:159], v[34:35], v[70:71] op_sel:[0,1,0]
	v_pk_fma_f32 v[34:35], v[156:157], v[34:35], v[100:101] op_sel:[0,1,0]
	s_nop 1
	s_waitcnt vmcnt(5)
	v_pk_fma_f32 v[42:43], v[160:161], v[44:45], v[42:43] op_sel_hi:[1,0,1]
	v_pk_fma_f32 v[6:7], v[160:161], v[8:9], v[6:7] op_sel_hi:[1,0,1]
	v_pk_fma_f32 v[10:11], v[160:161], v[12:13], v[10:11] op_sel_hi:[1,0,1]
	v_pk_fma_f32 v[14:15], v[160:161], v[16:17], v[14:15] op_sel_hi:[1,0,1]
	v_pk_fma_f32 v[18:19], v[160:161], v[20:21], v[18:19] op_sel_hi:[1,0,1]
	v_pk_fma_f32 v[22:23], v[160:161], v[24:25], v[22:23] op_sel_hi:[1,0,1]
	v_pk_fma_f32 v[26:27], v[160:161], v[28:29], v[26:27] op_sel_hi:[1,0,1]
	v_pk_fma_f32 v[30:31], v[160:161], v[32:33], v[30:31] op_sel_hi:[1,0,1]
	v_pk_fma_f32 v[34:35], v[160:161], v[36:37], v[34:35] op_sel_hi:[1,0,1]
	v_pk_fma_f32 v[48:49], v[162:163], v[44:45], v[48:49] op_sel_hi:[1,0,1]
	s_nop 0
	v_pk_fma_f32 v[46:47], v[162:163], v[8:9], v[46:47] op_sel_hi:[1,0,1]
	v_pk_fma_f32 v[50:51], v[162:163], v[12:13], v[50:51] op_sel_hi:[1,0,1]
	v_pk_fma_f32 v[52:53], v[162:163], v[16:17], v[52:53] op_sel_hi:[1,0,1]
	v_pk_fma_f32 v[54:55], v[162:163], v[20:21], v[54:55] op_sel_hi:[1,0,1]
	v_pk_fma_f32 v[64:65], v[162:163], v[24:25], v[64:65] op_sel_hi:[1,0,1]
	v_pk_fma_f32 v[66:67], v[162:163], v[28:29], v[66:67] op_sel_hi:[1,0,1]
	v_pk_fma_f32 v[68:69], v[162:163], v[32:33], v[68:69] op_sel_hi:[1,0,1]
	v_pk_fma_f32 v[70:71], v[162:163], v[36:37], v[70:71] op_sel_hi:[1,0,1]
	v_mov_b32_e32 v8, v45
	s_waitcnt vmcnt(4)
	v_pk_fma_f32 v[44:45], v[166:167], v[8:9], v[48:49] op_sel_hi:[1,0,1]
	v_pk_fma_f32 v[42:43], v[164:165], v[8:9], v[42:43] op_sel_hi:[1,0,1]
	v_mov_b32_e32 v8, v9
	v_pk_fma_f32 v[48:49], v[164:165], v[8:9], v[6:7] op_sel_hi:[1,0,1]
	v_mov_b32_e32 v6, v13
	v_pk_fma_f32 v[50:51], v[166:167], v[6:7], v[50:51] op_sel_hi:[1,0,1]
	v_pk_fma_f32 v[84:85], v[164:165], v[6:7], v[10:11] op_sel_hi:[1,0,1]
	v_mov_b32_e32 v6, v17
	v_pk_fma_f32 v[52:53], v[166:167], v[6:7], v[52:53] op_sel_hi:[1,0,1]
	v_pk_fma_f32 v[86:87], v[164:165], v[6:7], v[14:15] op_sel_hi:[1,0,1]
	v_mov_b32_e32 v6, v21
	v_pk_fma_f32 v[54:55], v[166:167], v[6:7], v[54:55] op_sel_hi:[1,0,1]
	v_pk_fma_f32 v[88:89], v[164:165], v[6:7], v[18:19] op_sel_hi:[1,0,1]
	v_mov_b32_e32 v6, v25
	v_pk_fma_f32 v[64:65], v[166:167], v[6:7], v[64:65] op_sel_hi:[1,0,1]
	v_pk_fma_f32 v[90:91], v[164:165], v[6:7], v[22:23] op_sel_hi:[1,0,1]
	v_mov_b32_e32 v6, v29
	v_pk_fma_f32 v[28:29], v[166:167], v[6:7], v[66:67] op_sel_hi:[1,0,1]
	v_pk_fma_f32 v[26:27], v[164:165], v[6:7], v[26:27] op_sel_hi:[1,0,1]
	v_mov_b32_e32 v6, v33
	v_pk_fma_f32 v[32:33], v[166:167], v[6:7], v[68:69] op_sel_hi:[1,0,1]
	v_pk_fma_f32 v[30:31], v[164:165], v[6:7], v[30:31] op_sel_hi:[1,0,1]
	v_mov_b32_e32 v6, v37
	v_pk_fma_f32 v[36:37], v[166:167], v[6:7], v[70:71] op_sel_hi:[1,0,1]
	v_pk_fma_f32 v[34:35], v[164:165], v[6:7], v[34:35] op_sel_hi:[1,0,1]
	v_pk_fma_f32 v[46:47], v[166:167], v[8:9], v[46:47] op_sel_hi:[1,0,1]
	s_nop 0
	ds_read_b128 v[6:9], v82 offset:8240
	ds_read_b128 v[10:13], v82 offset:16432
	ds_read_b128 v[14:17], v82 offset:24624
	ds_read_b128 v[18:21], v82 offset:32816
	s_waitcnt vmcnt(3) lgkmcnt(3)
	v_pk_fma_f32 v[70:71], v[168:169], v[6:7], v[48:49] op_sel_hi:[1,0,1]
	s_waitcnt lgkmcnt(2)
	v_pk_fma_f32 v[92:93], v[170:171], v[10:11], v[50:51] op_sel_hi:[1,0,1]
	ds_read_b128 v[48:51], v82 offset:57392
	s_waitcnt lgkmcnt(2)
	v_pk_fma_f32 v[94:95], v[170:171], v[14:15], v[52:53] op_sel_hi:[1,0,1]
	v_add_u32_e32 v52, 0x10030, v82
	v_pk_fma_f32 v[38:39], v[170:171], v[2:3], v[44:45] op_sel_hi:[1,0,1]
	v_pk_fma_f32 v[66:67], v[168:169], v[2:3], v[42:43] op_sel_hi:[1,0,1]
	v_pk_fma_f32 v[68:69], v[170:171], v[6:7], v[46:47] op_sel_hi:[1,0,1]
	ds_read_b128 v[40:43], v82 offset:41008
	ds_read_b128 v[44:47], v82 offset:49200
	s_waitcnt lgkmcnt(3)
	v_pk_fma_f32 v[96:97], v[170:171], v[18:19], v[54:55] op_sel_hi:[1,0,1]
	ds_read_b128 v[52:55], v52
	v_pk_fma_f32 v[84:85], v[168:169], v[10:11], v[84:85] op_sel_hi:[1,0,1]
	v_pk_fma_f32 v[86:87], v[168:169], v[14:15], v[86:87] op_sel_hi:[1,0,1]
	v_pk_fma_f32 v[88:89], v[168:169], v[18:19], v[88:89] op_sel_hi:[1,0,1]
	s_waitcnt lgkmcnt(2)
	v_pk_fma_f32 v[90:91], v[168:169], v[40:41], v[90:91] op_sel_hi:[1,0,1]
	s_waitcnt lgkmcnt(1)
	v_pk_fma_f32 v[26:27], v[168:169], v[44:45], v[26:27] op_sel_hi:[1,0,1]
	v_pk_fma_f32 v[30:31], v[168:169], v[48:49], v[30:31] op_sel_hi:[1,0,1]
	s_waitcnt lgkmcnt(0)
	v_pk_fma_f32 v[34:35], v[168:169], v[52:53], v[34:35] op_sel_hi:[1,0,1]
	v_pk_fma_f32 v[64:65], v[170:171], v[40:41], v[64:65] op_sel_hi:[1,0,1]
	s_nop 0
	v_pk_fma_f32 v[28:29], v[170:171], v[44:45], v[28:29] op_sel_hi:[1,0,1]
	v_pk_fma_f32 v[32:33], v[170:171], v[48:49], v[32:33] op_sel_hi:[1,0,1]
	v_pk_fma_f32 v[36:37], v[170:171], v[52:53], v[36:37] op_sel_hi:[1,0,1]
	s_waitcnt vmcnt(2)
	v_pk_fma_f32 v[38:39], v[174:175], v[2:3], v[38:39] op_sel:[0,1,0]
	v_pk_fma_f32 v[2:3], v[172:173], v[2:3], v[66:67] op_sel:[0,1,0]
	v_pk_fma_f32 v[82:83], v[174:175], v[6:7], v[68:69] op_sel:[0,1,0]
	v_pk_fma_f32 v[6:7], v[172:173], v[6:7], v[70:71] op_sel:[0,1,0]
	v_pk_fma_f32 v[70:71], v[174:175], v[10:11], v[92:93] op_sel:[0,1,0]
	v_pk_fma_f32 v[10:11], v[172:173], v[10:11], v[84:85] op_sel:[0,1,0]
	v_pk_fma_f32 v[84:85], v[174:175], v[14:15], v[94:95] op_sel:[0,1,0]
	v_pk_fma_f32 v[14:15], v[172:173], v[14:15], v[86:87] op_sel:[0,1,0]
	v_pk_fma_f32 v[86:87], v[174:175], v[18:19], v[96:97] op_sel:[0,1,0]
	v_pk_fma_f32 v[18:19], v[172:173], v[18:19], v[88:89] op_sel:[0,1,0]
	v_pk_fma_f32 v[88:89], v[174:175], v[40:41], v[64:65] op_sel:[0,1,0]
	v_pk_fma_f32 v[40:41], v[172:173], v[40:41], v[90:91] op_sel:[0,1,0]
	v_pk_fma_f32 v[90:91], v[174:175], v[44:45], v[28:29] op_sel:[0,1,0]
	v_pk_fma_f32 v[44:45], v[172:173], v[44:45], v[26:27] op_sel:[0,1,0]
	v_pk_fma_f32 v[94:95], v[172:173], v[48:49], v[30:31] op_sel:[0,1,0]
	v_pk_fma_f32 v[98:99], v[172:173], v[52:53], v[34:35] op_sel:[0,1,0]
	v_pk_fma_f32 v[96:97], v[174:175], v[52:53], v[36:37] op_sel:[0,1,0]
	s_nop 0
	v_pk_fma_f32 v[92:93], v[174:175], v[48:49], v[32:33] op_sel:[0,1,0]
	s_waitcnt vmcnt(1)
	v_pk_fma_f32 v[52:53], v[176:177], v[42:43], v[40:41] op_sel_hi:[1,0,1]
	v_pk_fma_f32 v[36:37], v[178:179], v[4:5], v[38:39] op_sel_hi:[1,0,1]
	s_nop 0
	v_pk_fma_f32 v[38:39], v[176:177], v[4:5], v[2:3] op_sel_hi:[1,0,1]
	v_pk_fma_f32 v[32:33], v[178:179], v[8:9], v[82:83] op_sel_hi:[1,0,1]
	v_pk_fma_f32 v[34:35], v[176:177], v[8:9], v[6:7] op_sel_hi:[1,0,1]
	v_pk_fma_f32 v[28:29], v[178:179], v[12:13], v[70:71] op_sel_hi:[1,0,1]
	v_pk_fma_f32 v[30:31], v[176:177], v[12:13], v[10:11] op_sel_hi:[1,0,1]
	v_pk_fma_f32 v[24:25], v[178:179], v[16:17], v[84:85] op_sel_hi:[1,0,1]
	v_pk_fma_f32 v[26:27], v[176:177], v[16:17], v[14:15] op_sel_hi:[1,0,1]
	v_pk_fma_f32 v[22:23], v[178:179], v[20:21], v[86:87] op_sel_hi:[1,0,1]
	v_pk_fma_f32 v[64:65], v[176:177], v[20:21], v[18:19] op_sel_hi:[1,0,1]
	v_pk_fma_f32 v[18:19], v[178:179], v[42:43], v[88:89] op_sel_hi:[1,0,1]
	v_pk_fma_f32 v[14:15], v[178:179], v[46:47], v[90:91] op_sel_hi:[1,0,1]
	v_pk_fma_f32 v[48:49], v[176:177], v[46:47], v[44:45] op_sel_hi:[1,0,1]
	v_pk_fma_f32 v[10:11], v[178:179], v[50:51], v[92:93] op_sel_hi:[1,0,1]
	v_pk_fma_f32 v[44:45], v[176:177], v[50:51], v[94:95] op_sel_hi:[1,0,1]
	v_pk_fma_f32 v[2:3], v[178:179], v[54:55], v[96:97] op_sel_hi:[1,0,1]
	v_pk_fma_f32 v[6:7], v[176:177], v[54:55], v[98:99] op_sel_hi:[1,0,1]
	v_mov_b32_e32 v4, v5
	s_mov_b64 s[0:1], 0xc0000
	v_lshl_add_u64 v[62:63], v[62:63], 0, s[0:1]
	s_waitcnt vmcnt(0)
	v_pk_fma_f32 v[40:41], v[190:191], v[4:5], v[36:37] op_sel_hi:[1,0,1]
	v_pk_fma_f32 v[38:39], v[188:189], v[4:5], v[38:39] op_sel_hi:[1,0,1]
	v_mov_b32_e32 v4, v9
	v_pk_fma_f32 v[36:37], v[190:191], v[4:5], v[32:33] op_sel_hi:[1,0,1]
	v_pk_fma_f32 v[34:35], v[188:189], v[4:5], v[34:35] op_sel_hi:[1,0,1]
	v_mov_b32_e32 v4, v13
	v_pk_fma_f32 v[32:33], v[190:191], v[4:5], v[28:29] op_sel_hi:[1,0,1]
	v_pk_fma_f32 v[30:31], v[188:189], v[4:5], v[30:31] op_sel_hi:[1,0,1]
	v_mov_b32_e32 v4, v17
	v_pk_fma_f32 v[28:29], v[190:191], v[4:5], v[24:25] op_sel_hi:[1,0,1]
	v_pk_fma_f32 v[26:27], v[188:189], v[4:5], v[26:27] op_sel_hi:[1,0,1]
	v_mov_b32_e32 v4, v21
	v_pk_fma_f32 v[24:25], v[190:191], v[4:5], v[22:23] op_sel_hi:[1,0,1]
	v_pk_fma_f32 v[22:23], v[188:189], v[4:5], v[64:65] op_sel_hi:[1,0,1]
	v_mov_b32_e32 v4, v43
	v_pk_fma_f32 v[20:21], v[190:191], v[4:5], v[18:19] op_sel_hi:[1,0,1]
	v_pk_fma_f32 v[18:19], v[188:189], v[4:5], v[52:53] op_sel_hi:[1,0,1]
	v_mov_b32_e32 v4, v47
	v_pk_fma_f32 v[16:17], v[190:191], v[4:5], v[14:15] op_sel_hi:[1,0,1]
	v_pk_fma_f32 v[14:15], v[188:189], v[4:5], v[48:49] op_sel_hi:[1,0,1]
	v_mov_b32_e32 v4, v51
	v_pk_fma_f32 v[12:13], v[190:191], v[4:5], v[10:11] op_sel_hi:[1,0,1]
	v_pk_fma_f32 v[10:11], v[188:189], v[4:5], v[44:45] op_sel_hi:[1,0,1]
	v_mov_b32_e32 v4, v55
	v_pk_fma_f32 v[8:9], v[190:191], v[4:5], v[2:3] op_sel_hi:[1,0,1]
	v_pk_fma_f32 v[6:7], v[188:189], v[4:5], v[6:7] op_sel_hi:[1,0,1]
	s_cbranch_scc1 .LBB0_27
	ds_write_b128 v56, v[38:41]
	ds_write_b128 v56, v[34:37] offset:512
	ds_write_b128 v56, v[30:33] offset:1024
	ds_write_b128 v56, v[26:29] offset:1536
	ds_write_b128 v56, v[22:25] offset:2048
	ds_write_b128 v56, v[18:21] offset:2560
	ds_write_b128 v56, v[14:17] offset:3072
	ds_write_b128 v56, v[10:13] offset:3584
	ds_write_b128 v56, v[6:9] offset:4096
	s_waitcnt lgkmcnt(0)
	s_barrier
	s_and_saveexec_b64 s[2:3], vcc
	s_cbranch_execz .LBB0_25
	s_mul_i32 s0, s16, 0x3000
	s_add_i32 s0, s0, s6
	v_or_b32_e32 v2, s0, v80
	v_ashrrev_i32_e32 v3, 31, v2
	s_mul_i32 s16, s16, 9
	v_lshl_add_u64 v[2:3], v[2:3], 2, s[52:53]
	v_lshl_add_u64 v[4:5], s[6:7], 2, v[58:59]
	s_mov_b64 s[6:7], 0
	v_mov_b32_e32 v6, v1
